# diff attention restructured: K/V tiles double-buffered in LDS and staged by LDS-DMA (no staging VGPRs / ds_write phase, one barrier per tile), Q fragments kept in registers
# speedup vs baseline: 1.0182x; 1.0182x over previous
.LBB0_396:
	s_or_b32 s4, s4, s90
	s_mul_i32 s4, s4, 0x102000
	s_add_i32 s44, s91, s4
	s_xor_b64 s[50:51], s[52:53], -1
	v_mbcnt_lo_u32_b32 v32, -1, 0
	v_mbcnt_hi_u32_b32 v32, -1, v32
	s_lshl_b32 s100, s3, 10
	v_lshrrev_b32_e32 v236, 4, v32
	s_lshl_b32 s97, s3, 2
	v_add_u32_e32 v236, s97, v236
	v_and_b32_e32 v237, 15, v32
	v_and_b32_e32 v238, 7, v236
	v_xor_b32_e32 v237, v237, v238
	v_lshlrev_b32_e32 v232, 8, v236
	v_lshl_or_b32 v232, v237, 4, v232
	v_add_u32_e32 v233, 0x2000, v232
	s_lshr_b32 s98, s3, 1
	s_lshl_b32 s98, s98, 3
	v_bfe_u32 v236, v32, 2, 3
	v_add_u32_e32 v236, s98, v236
	s_and_b32 s99, s3, 1
	s_lshl_b32 s99, s99, 1
	v_lshrrev_b32_e32 v237, 5, v32
	v_add_u32_e32 v237, s99, v237
	v_and_b32_e32 v238, 3, v32
	v_lshlrev_b32_e32 v238, 4, v238
	v_lshl_or_b32 v238, v237, 6, v238
	v_lshl_or_b32 v234, v236, 8, v238
	v_add_u32_e32 v235, 0x2000, v234
	s_lshl_b64 s[54:55], s[44:45], 1
	v_and_b32_e32 v198, 31, v32
	s_add_u32 s54, s26, s54
	v_or_b32_e32 v184, s40, v198
	v_bfe_u32 v199, v32, 5, 1
	s_addc_u32 s55, s27, s55
	v_lshlrev_b64 v[0:1], 8, v[184:185]
	v_lshl_add_u64 v[0:1], s[54:55], 0, v[0:1]
	v_lshlrev_b32_e32 v184, 4, v199
	v_lshl_add_u64 v[28:29], v[0:1], 0, v[184:185]
	global_load_dwordx4 v[160:163], v[28:29], off
	global_load_dwordx4 v[164:167], v[28:29], off offset:32
	global_load_dwordx4 v[168:171], v[28:29], off offset:64
	global_load_dwordx4 v[172:175], v[28:29], off offset:96
	global_load_dwordx4 v[176:179], v[28:29], off offset:128
	global_load_dwordx4 v[180:183], v[28:29], off offset:160
	global_load_dwordx4 v[240:243], v[28:29], off offset:192
	s_nop 0
	global_load_dwordx4 v[244:247], v[28:29], off offset:224
	v_add_u32_e32 v40, s64, v32
	v_and_b32_e32 v195, 63, v32
	v_lshlrev_b32_e32 v41, 3, v32
	s_mov_b32 s5, s45
	v_lshlrev_b32_e32 v34, 1, v32
	v_ashrrev_i32_e32 v42, 4, v40
	v_and_b32_e32 v43, 0x78, v41
	v_lshlrev_b32_e32 v196, 4, v195
	v_lshlrev_b32_e32 v36, 4, v32
	v_lshlrev_b32_e32 v197, 3, v195
	v_and_b32_e32 v37, 32, v34
	v_and_b32_e32 v34, 0xc0, v196
	v_lshl_or_b32 v32, v42, 7, v43
	s_lshl_b64 s[4:5], s[4:5], 1
	v_mov_b32_e32 v35, v185
	v_lshlrev_b32_e32 v44, 8, v198
	v_and_or_b32 v39, v197, 24, v34
	v_add_u32_e32 v34, 0x1000, v32
	s_add_u32 s4, s26, s4
	v_mov_b32_e32 v33, v185
	v_and_b32_e32 v45, 0x70, v36
	v_and_b32_e32 v38, 0x100, v197
	v_add_u32_e32 v46, s9, v44
	v_bitop3_b32 v36, v184, v36, s71 bitop3:0x78
	v_lshlrev_b64 v[188:189], 1, v[34:35]
	s_addc_u32 s5, s27, s5
	v_lshlrev_b64 v[186:187], 1, v[32:33]
	v_or3_b32 v56, v39, v37, v38
	v_add_u32_e32 v57, v46, v36
	s_add_u32 s54, s4, 0x4080000
	s_addc_u32 s55, s5, 0
	s_add_i32 s99, s100, 0x8000
	s_mov_b32 m0, s99
	s_nop 0
	global_load_lds_dwordx4 v232, s[54:55]
	s_add_i32 m0, s99, 0x2000
	s_nop 0
	global_load_lds_dwordx4 v233, s[54:55]
	s_mov_b32 m0, s100
	s_nop 0
	global_load_lds_dwordx4 v234, s[48:49]
	s_add_i32 m0, s100, 0x2000
	s_nop 0
	global_load_lds_dwordx4 v235, s[48:49]
	s_add_i32 m0, s100, 0x4000
	s_nop 0
	global_load_lds_dwordx4 v234, s[6:7]
	s_add_i32 m0, s100, 0x6000
	s_nop 0
	global_load_lds_dwordx4 v235, s[6:7]
	s_movk_i32 s14, 0x60
	v_bitop3_b32 v48, v184, v45, 32 bitop3:0x36
	v_bitop3_b32 v50, v184, v45, 64 bitop3:0x36
	v_bitop3_b32 v52, v184, v45, s14 bitop3:0x36
	v_or_b32_e32 v53, 0x80, v184
	v_or_b32_e32 v54, 0xa0, v184
	v_or_b32_e32 v55, 0xc0, v184
	v_add_u32_e32 v48, v46, v48
	v_add_u32_e32 v50, v46, v50
	v_add_u32_e32 v52, v46, v52
	v_xad_u32 v53, v53, v45, v46
	v_xad_u32 v54, v54, v45, v46
	v_xad_u32 v55, v55, v45, v46
	s_cmp_lg_u32 0, -1
	s_cselect_b32 s4, 0, 0
	v_add_u32_e32 v200, s4, v56
	s_add_i32 s4, 0, 0x8000
	s_cmp_lg_u32 s4, -1
	v_or_b32_e32 v47, 32, v184
	s_cselect_b32 s4, s4, 0
	v_or_b32_e32 v49, 64, v184
	v_or_b32_e32 v51, 0x60, v184
	v_mov_b32_e32 v64, v185
	v_mov_b32_e32 v65, v185
	v_mov_b32_e32 v78, v185
	v_mov_b32_e32 v79, v185
	v_mov_b32_e32 v66, v185
	v_mov_b32_e32 v67, v185
	v_mov_b32_e32 v68, v185
	v_mov_b32_e32 v69, v185
	v_mov_b32_e32 v70, v185
	v_mov_b32_e32 v71, v185
	v_lshrrev_b32_e32 v4, 1, v42
	v_and_b32_e32 v5, 3, v42
	v_and_or_b32 v4, v4, 4, v5
	v_add_u32_e32 v5, 32, v42
	v_lshlrev_b32_e32 v2, 1, v42
	v_and_b32_e32 v3, 0xfffff0, v42
	v_lshlrev_b32_e32 v6, 1, v5
	v_and_b32_e32 v5, 0xfffff0, v5
	v_or_b32_e32 v0, 0xe0, v184
	v_and_or_b32 v2, v2, 8, v3
	v_and_or_b32 v5, v6, 8, v5
	v_xad_u32 v0, v0, v45, v46
	v_lshrrev_b32_e32 v2, 1, v2
	v_bfe_u32 v3, v41, 5, 2
	v_lshrrev_b32_e32 v5, 1, v5
	v_lshlrev_b32_e32 v0, 1, v43
	v_or_b32_e32 v2, v2, v3
	v_or_b32_e32 v3, v5, v3
	v_bitop3_b32 v1, v0, v40, s71 bitop3:0x78
	v_lshlrev_b32_e32 v2, 9, v2
	v_lshlrev_b32_e32 v4, 6, v4
	v_and_b32_e32 v0, 48, v0
	v_lshlrev_b32_e32 v3, 9, v3
	v_or3_b32 v2, v2, v4, v0
	v_or3_b32 v0, v3, v4, v0
	v_bitop3_b32 v4, v184, v44, v45 bitop3:0xde
	v_add_u32_e32 v201, s4, v4
	v_add_u32_e32 v202, s61, v4
	v_bitop3_b32 v4, v47, v44, v45 bitop3:0xde
	v_add_u32_e32 v203, s4, v4
	v_add_u32_e32 v204, s61, v4
	v_bitop3_b32 v4, v49, v44, v45 bitop3:0xde
	v_lshl_add_u32 v3, v42, 8, 0
	v_add_u32_e32 v206, s4, v4
	v_add_u32_e32 v207, s61, v4
	v_bitop3_b32 v4, v51, v44, v45 bitop3:0xde
	v_add_u32_e32 v208, s4, v4
	v_add_u32_e32 v209, s61, v4
	v_mov_b32_e32 v72, v185
	v_mov_b32_e32 v73, v185
	v_mov_b32_e32 v74, v185
	v_mov_b32_e32 v75, v185
	v_mov_b32_e32 v76, v185
	v_mov_b32_e32 v77, v185
	v_add_u32_e32 v211, v3, v1
	v_mov_b64_e32 v[126:127], v[78:79]
	v_mov_b64_e32 v[110:111], v[78:79]
	v_mov_b64_e32 v[94:95], v[78:79]
	v_mov_b64_e32 v[48:49], v[64:65]
	v_mov_b64_e32 v[32:33], v[64:65]
	v_mov_b64_e32 v[16:17], v[64:65]
	v_mov_b64_e32 v[0:1], v[64:65]
	s_mov_b32 s44, 64
	v_cmp_gt_u32_e64 s[4:5], 32, v195
	v_lshl_add_u32 v205, v198, 2, s63
	v_mov_b32_e32 v214, 0
	v_mov_b32_e32 v210, 0xf149f2ca
	v_mov_b64_e32 v[124:125], v[76:77]
	v_mov_b64_e32 v[122:123], v[74:75]
	v_mov_b64_e32 v[120:121], v[72:73]
	v_mov_b64_e32 v[118:119], v[70:71]
	v_mov_b64_e32 v[116:117], v[68:69]
	v_mov_b64_e32 v[114:115], v[66:67]
	v_mov_b64_e32 v[112:113], v[64:65]
	v_mov_b64_e32 v[108:109], v[76:77]
	v_mov_b64_e32 v[106:107], v[74:75]
	v_mov_b64_e32 v[104:105], v[72:73]
	v_mov_b64_e32 v[102:103], v[70:71]
	v_mov_b64_e32 v[100:101], v[68:69]
	v_mov_b64_e32 v[98:99], v[66:67]
	v_mov_b64_e32 v[96:97], v[64:65]
	v_mov_b64_e32 v[92:93], v[76:77]
	v_mov_b64_e32 v[90:91], v[74:75]
	v_mov_b64_e32 v[88:89], v[72:73]
	v_mov_b64_e32 v[86:87], v[70:71]
	v_mov_b64_e32 v[84:85], v[68:69]
	v_mov_b64_e32 v[82:83], v[66:67]
	v_mov_b64_e32 v[80:81], v[64:65]
	v_mov_b64_e32 v[50:51], v[66:67]
	v_mov_b64_e32 v[52:53], v[68:69]
	v_mov_b64_e32 v[54:55], v[70:71]
	v_mov_b64_e32 v[56:57], v[72:73]
	v_mov_b64_e32 v[58:59], v[74:75]
	v_mov_b64_e32 v[60:61], v[76:77]
	v_mov_b64_e32 v[62:63], v[78:79]
	v_mov_b64_e32 v[34:35], v[66:67]
	v_mov_b64_e32 v[36:37], v[68:69]
	v_mov_b64_e32 v[38:39], v[70:71]
	v_mov_b64_e32 v[40:41], v[72:73]
	v_mov_b64_e32 v[42:43], v[74:75]
	v_mov_b64_e32 v[44:45], v[76:77]
	v_mov_b64_e32 v[46:47], v[78:79]
	v_mov_b64_e32 v[18:19], v[66:67]
	v_mov_b64_e32 v[20:21], v[68:69]
	v_mov_b64_e32 v[22:23], v[70:71]
	v_mov_b64_e32 v[24:25], v[72:73]
	v_mov_b64_e32 v[26:27], v[74:75]
	v_mov_b64_e32 v[28:29], v[76:77]
	v_mov_b64_e32 v[30:31], v[78:79]
	v_mov_b64_e32 v[2:3], v[66:67]
	v_mov_b64_e32 v[4:5], v[68:69]
	v_mov_b64_e32 v[6:7], v[70:71]
	v_mov_b64_e32 v[8:9], v[72:73]
	v_mov_b64_e32 v[10:11], v[74:75]
	v_mov_b64_e32 v[12:13], v[76:77]
	v_mov_b64_e32 v[14:15], v[78:79]
	s_mov_b32 s56, 0
.LBB0_397:
	s_waitcnt vmcnt(0)
	s_add_i32 s96, s56, 1
	s_cmp_ge_i32 s96, s93
	s_waitcnt lgkmcnt(0)
	s_barrier
	s_cbranch_scc1 .LBB0_399
	s_lshl_b64 vcc, s[44:45], 8
	s_add_u32 s24, s54, vcc_lo
	s_addc_u32 s25, s55, vcc_hi
	s_add_u32 s14, s48, vcc_lo
	s_addc_u32 s15, s49, vcc_hi
	s_and_b32 s97, s96, 1
	s_mul_i32 s98, s97, 0xc000
	s_add_i32 s98, s98, s100
	s_add_i32 s99, s98, 0x8000
	s_mov_b32 m0, s99
	s_nop 0
	global_load_lds_dwordx4 v232, s[24:25]
	s_add_i32 m0, s99, 0x2000
	s_nop 0
	global_load_lds_dwordx4 v233, s[24:25]
	s_mov_b32 m0, s98
	s_nop 0
	global_load_lds_dwordx4 v234, s[14:15]
	s_add_i32 m0, s98, 0x2000
	s_nop 0
	global_load_lds_dwordx4 v235, s[14:15]
	s_add_u32 s24, s6, vcc_lo
	s_addc_u32 s25, s7, vcc_hi
	s_add_i32 m0, s98, 0x4000
	s_nop 0
	global_load_lds_dwordx4 v234, s[24:25]
	s_add_i32 m0, s98, 0x6000
	s_nop 0
	global_load_lds_dwordx4 v235, s[24:25]
.LBB0_399:
	s_cmp_ge_i32 s56, s94
	s_cbranch_scc1 .LBB0_405
	ds_read_b128 v[128:131], v201 offset:0
	ds_read_b128 v[148:151], v201 offset:0x2000
	ds_read_b128 v[216:219], v203 offset:0
	ds_read_b128 v[220:223], v203 offset:0x2000
	s_waitcnt lgkmcnt(2)
	s_nop 0
	v_mfma_f32_32x32x16_bf16 v[128:143], v[128:131], v[160:163], 0
	v_mfma_f32_32x32x16_bf16 v[144:159], v[148:151], v[160:163], 0
	ds_read_b128 v[224:227], v206 offset:0
	ds_read_b128 v[228:231], v206 offset:0x2000
	s_waitcnt lgkmcnt(2)
	v_mfma_f32_32x32x16_bf16 v[128:143], v[216:219], v[164:167], v[128:143]
	v_mfma_f32_32x32x16_bf16 v[144:159], v[220:223], v[164:167], v[144:159]
	ds_read_b128 v[216:219], v208 offset:0
	ds_read_b128 v[220:223], v208 offset:0x2000
	s_waitcnt lgkmcnt(2)
	v_mfma_f32_32x32x16_bf16 v[128:143], v[224:227], v[168:171], v[128:143]
	v_mfma_f32_32x32x16_bf16 v[144:159], v[228:231], v[168:171], v[144:159]
	ds_read_b128 v[224:227], v201 offset:0x80
	ds_read_b128 v[228:231], v201 offset:0x2080
	s_waitcnt lgkmcnt(2)
	v_mfma_f32_32x32x16_bf16 v[128:143], v[216:219], v[172:175], v[128:143]
	v_mfma_f32_32x32x16_bf16 v[144:159], v[220:223], v[172:175], v[144:159]
	ds_read_b128 v[216:219], v203 offset:0x80
	ds_read_b128 v[220:223], v203 offset:0x2080
	s_waitcnt lgkmcnt(2)
	v_mfma_f32_32x32x16_bf16 v[128:143], v[224:227], v[176:179], v[128:143]
	v_mfma_f32_32x32x16_bf16 v[144:159], v[228:231], v[176:179], v[144:159]
	ds_read_b128 v[224:227], v206 offset:0x80
	ds_read_b128 v[228:231], v206 offset:0x2080
	s_waitcnt lgkmcnt(2)
	v_mfma_f32_32x32x16_bf16 v[128:143], v[216:219], v[180:183], v[128:143]
	v_mfma_f32_32x32x16_bf16 v[144:159], v[220:223], v[180:183], v[144:159]
	ds_read_b128 v[216:219], v208 offset:0x80
	ds_read_b128 v[220:223], v208 offset:0x2080
	s_waitcnt lgkmcnt(2)
	v_mfma_f32_32x32x16_bf16 v[128:143], v[224:227], v[240:243], v[128:143]
	v_mfma_f32_32x32x16_bf16 v[144:159], v[228:231], v[240:243], v[144:159]
	s_waitcnt lgkmcnt(0)
	v_mfma_f32_32x32x16_bf16 v[128:143], v[216:219], v[244:247], v[128:143]
	s_cmp_eq_u32 s56, 0
	s_cselect_b64 vcc, -1, 0
	s_mov_b32 s14, 0x41000000
	v_mfma_f32_32x32x16_bf16 v[144:159], v[220:223], v[244:247], v[144:159]
	s_cbranch_scc1 .Ldiff_pad
	s_nop 7
	v_max_f32_e32 v215, v128, v129
	v_max3_f32 v215, v215, v130, v131
	v_max3_f32 v215, v215, v132, v133
	v_max3_f32 v215, v215, v134, v135
	v_max3_f32 v215, v215, v136, v137
	v_max3_f32 v215, v215, v138, v139
	v_max3_f32 v215, v215, v140, v141
	v_max3_f32 v215, v215, v142, v143
	v_max3_f32 v215, v215, v144, v145
	v_max3_f32 v215, v215, v146, v147
	v_max3_f32 v215, v215, v148, v149
	v_max3_f32 v215, v215, v150, v151
	v_max3_f32 v215, v215, v152, v153
	v_max3_f32 v215, v215, v154, v155
	v_max3_f32 v215, v215, v156, v157
	v_max3_f32 v215, v215, v158, v159
	s_branch .Ldiff_padjoin

.LBB0_405:
	v_xor_b32_e32 v200, 0xc000, v200
	v_xor_b32_e32 v201, 0x1c000, v201
	v_xor_b32_e32 v203, 0x1c000, v203
	v_xor_b32_e32 v206, 0x1c000, v206
	v_xor_b32_e32 v208, 0x1c000, v208
	s_add_i32 s44, s44, 64
	s_cmp_eq_u32 s95, s96
	s_cbranch_scc1 .LBB0_407
	s_mov_b32 s56, s96
	s_branch .LBB0_397

.LBB0_407:
	s_barrier
	s_and_saveexec_b64 s[54:55], s[4:5]
	s_cbranch_execz .LBB0_395
	ds_write_b32 v205, v214
	s_branch .LBB0_395

	.amdhsa_kernel _Z6mk_fwd4Args
		.amdhsa_group_segment_fixed_size 0
		.amdhsa_private_segment_fixed_size 0
		.amdhsa_kernarg_size 424
		.amdhsa_user_sgpr_count 2
		.amdhsa_user_sgpr_dispatch_ptr 0
		.amdhsa_user_sgpr_queue_ptr 0
		.amdhsa_user_sgpr_kernarg_segment_ptr 1
		.amdhsa_user_sgpr_dispatch_id 0
		.amdhsa_user_sgpr_kernarg_preload_length 0
		.amdhsa_user_sgpr_kernarg_preload_offset 0
		.amdhsa_user_sgpr_private_segment_size 0
		.amdhsa_uses_dynamic_stack 0
		.amdhsa_enable_private_segment 0
		.amdhsa_system_sgpr_workgroup_id_x 1
		.amdhsa_system_sgpr_workgroup_id_y 0
		.amdhsa_system_sgpr_workgroup_id_z 0
		.amdhsa_system_sgpr_workgroup_info 0
		.amdhsa_system_vgpr_workitem_id 0
		.amdhsa_next_free_vgpr 256
		.amdhsa_next_free_sgpr 102
		.amdhsa_accum_offset 256
		.amdhsa_reserve_vcc 1
		.amdhsa_float_round_mode_32 0
		.amdhsa_float_round_mode_16_64 0
		.amdhsa_float_denorm_mode_32 3
		.amdhsa_float_denorm_mode_16_64 3
		.amdhsa_dx10_clamp 1
		.amdhsa_ieee_mode 1
		.amdhsa_fp16_overflow 0
		.amdhsa_tg_split 0
		.amdhsa_exception_fp_ieee_invalid_op 0
		.amdhsa_exception_fp_denorm_src 0
		.amdhsa_exception_fp_ieee_div_zero 0
		.amdhsa_exception_fp_ieee_overflow 0
		.amdhsa_exception_fp_ieee_underflow 0
		.amdhsa_exception_fp_ieee_inexact 0
		.amdhsa_exception_int_div_zero 0
	.end_amdhsa_kernel

amdhsa.kernels:
  - .agpr_count:     0
    .args:
      - .offset:         0
        .size:           168
        .value_kind:     by_value
      - .offset:         168
        .size:           4
        .value_kind:     hidden_block_count_x
      - .offset:         172
        .size:           4
        .value_kind:     hidden_block_count_y
      - .offset:         176
        .size:           4
        .value_kind:     hidden_block_count_z
      - .offset:         180
        .size:           2
        .value_kind:     hidden_group_size_x
      - .offset:         182
        .size:           2
        .value_kind:     hidden_group_size_y
      - .offset:         184
        .size:           2
        .value_kind:     hidden_group_size_z
      - .offset:         186
        .size:           2
        .value_kind:     hidden_remainder_x
      - .offset:         188
        .size:           2
        .value_kind:     hidden_remainder_y
      - .offset:         190
        .size:           2
        .value_kind:     hidden_remainder_z
      - .offset:         208
        .size:           8
        .value_kind:     hidden_global_offset_x
      - .offset:         216
        .size:           8
        .value_kind:     hidden_global_offset_y
      - .offset:         224
        .size:           8
        .value_kind:     hidden_global_offset_z
      - .offset:         232
        .size:           2
        .value_kind:     hidden_grid_dims
      - .offset:         288
        .size:           4
        .value_kind:     hidden_dynamic_lds_size
    .group_segment_fixed_size: 0
    .kernarg_segment_align: 8
    .kernarg_segment_size: 424
    .language:       OpenCL C
    .language_version:
      - 2
      - 0
    .max_flat_workgroup_size: 512
    .name:           _Z6mk_fwd4Args
    .private_segment_fixed_size: 0
    .sgpr_count:     108
    .sgpr_spill_count: 4
    .symbol:         _Z6mk_fwd4Args.kd
    .uniform_work_group_size: 1
    .uses_dynamic_stack: false
    .vgpr_count:     256
    .vgpr_spill_count: 0
    .wavefront_size: 64
